# QKV-GEMM k-loop given the same load-segment recipe as the up-GEMM loop (4/4/4/4 staging, SGPR-base DMA, DMA/ds_read interleave, early m0)
# baseline (speedup 1.0000x reference)
; #define PG8_STAGE(bufoff, gbase, voff) do { _Pragma("unroll") for (int _i = 0; _i < 2; ++_i) \
;         __builtin_amdgcn_global_load_lds((const unsigned*)((const char*)(gbase) + (voff)[_i]), (LAS unsigned*)(lds + (bufoff) + ldsw + _i * 8192), 16, 0, 0); } while (0)
; #define PG8_LDA(dst, b, h) do { _Pragma("unroll") for (int m = 0; m < 4; ++m) _Pragma("unroll") for (int k = 0; k < 2; ++k) dst[m][k] = *(const LAS bf16x8*)(lds + PG8_SA(b, h) + aoff + m * 2048 + k * 1024); } while (0)
; #define PG8_LDB(dst, b, h) do { _Pragma("unroll") for (int n = 0; n < 2; ++n) _Pragma("unroll") for (int k = 0; k < 2; ++k) dst[n][k] = *(const LAS bf16x8*)(lds + PG8_SB(b, h) + boff + n * 2048 + k * 1024); } while (0)
; #define PG8_MMA(ai, bj, At, Bt) do { __builtin_amdgcn_s_setprio(1); _Pragma("unroll") for (int m = 0; m < 4; ++m) _Pragma("unroll") for (int n = 0; n < 2; ++n) _Pragma("unroll") for (int k = 0; k < 2; ++k) \
;         acc[ai][bj][m][n] = __builtin_amdgcn_mfma_f32_16x16x32_bf16(Bt[n][k], At[m][k], acc[ai][bj][m][n], 0, 0, 0); __builtin_amdgcn_s_setprio(0); } while (0)
; #define PG8_WAIT_V(n) asm volatile("s_waitcnt vmcnt(" #n ")" ::: "memory")
; #define PG8_WAIT_L(n) asm volatile("s_waitcnt lgkmcnt(" #n ")" ::: "memory")
; #define PG8_BAR __builtin_amdgcn_s_barrier()
; template <class Epi, class Sched, bool ALIGN_EPI = false, bool SP2 = false>
; __device__ __forceinline__ void gemm_phase(LAS unsigned char* lds, const Gemm g, const Sched& S, const Epi& E, int wid) {
;     ...
;         for (int t = 0; t < nt; t += 2) {
;             const bool last = (t == nt - 2);
;             const char* a1 = cA + (size_t)(t + 1) * kstep;
;             const char* a2 = last ? nA : cA + (size_t)(t + 2) * kstep; const char* b2 = last ? nB : cB + (size_t)(t + 2) * kstep;
;             const char* a3 = a2 + kstep; const char* b3 = b2 + kstep;
;             if constexpr (SP2) {
;             PG8_LDB(B0, 0, 0); PG8_LDB(B1, 0, 1); PG8_SCHED; PG8_LDA(At, 0, 0); PG8_STAGE(PG8_SA(1, 1), a1 + hstepA, voffA);
;             PG8_WAIT_V(8); PG8_WAIT_L(0); PG8_BAR; PG8_MMA(0, 0, At, B0); PG8_MMA(0, 1, At, B1); PG8_BAR; PG8_SCHED;
;             PG8_LDA(At, 0, 1); PG8_STAGE(PG8_SB(0, 0), b2, voffB); PG8_STAGE(PG8_SB(0, 1), b2 + hstepB, voffB); PG8_STAGE(PG8_SA(0, 0), a2, voffA);
;             PG8_WAIT_V(8); PG8_WAIT_L(0); PG8_BAR; PG8_MMA(1, 0, At, B0); PG8_MMA(1, 1, At, B1); PG8_BAR; PG8_SCHED;
.LBB0_488:
	s_add_u32 s30, s10, 0xfff80080
	s_addc_u32 s31, s11, -1
	s_add_i32 s55, 0, 0x10000
	s_cmp_eq_u32 s54, 28
	s_cselect_b32 s35, s6, s31
	s_cselect_b32 s34, s7, s30
	s_cselect_b32 s31, s27, s53
	s_cselect_b32 s30, s45, s47
	s_add_i32 s58, 0, 0x14000
	v_add_u32_e32 v154, s55, v147
	v_add_u32_e32 v170, s58, v147
	s_add_i32 m0, s42, 0xc000
	s_add_u32 s100, s10, 0xfff80000
	s_addc_u32 s101, s11, -1
	s_mov_b32 m0, s50
	s_nop 0
	global_load_lds_dwordx4 v132, s[100:101]
	s_mov_b32 m0, s51
	ds_read_b128 v[138:141], v154
	ds_read_b128 v[142:145], v154 offset:1024
	ds_read_b128 v[150:153], v154 offset:2048
	ds_read_b128 v[154:157], v154 offset:3072
	global_load_lds_dwordx4 v130, s[100:101]
	s_add_i32 m0, s42, 0xc000
	ds_read_b128 v[158:161], v170
	ds_read_b128 v[162:165], v170 offset:1024
	ds_read_b128 v[166:169], v170 offset:2048
	ds_read_b128 v[170:173], v170 offset:3072
	global_load_lds_dwordx4 v134, s[10:11]
	s_add_i32 m0, s42, 0xe000
	ds_read_b128 v[174:177], v149
	ds_read_b128 v[178:181], v149 offset:1024
	ds_read_b128 v[182:185], v149 offset:2048
	ds_read_b128 v[186:189], v149 offset:3072
	global_load_lds_dwordx4 v136, s[10:11]
	ds_read_b128 v[200:203], v149 offset:4096
	ds_read_b128 v[204:207], v149 offset:5120
	ds_read_b128 v[208:211], v149 offset:6144
	ds_read_b128 v[212:215], v149 offset:7168
	s_waitcnt vmcnt(8)
	s_waitcnt lgkmcnt(0)
	s_barrier
	s_setprio 1
	s_waitcnt lgkmcnt(0)
	v_mfma_f32_16x16x32_bf16 v[124:127], v[138:141], v[174:177], v[124:127]
	v_mfma_f32_16x16x32_bf16 v[120:123], v[150:153], v[174:177], v[120:123]
	v_mfma_f32_16x16x32_bf16 v[108:111], v[138:141], v[182:185], v[108:111]
	v_mfma_f32_16x16x32_bf16 v[104:107], v[150:153], v[182:185], v[104:107]
	v_mfma_f32_16x16x32_bf16 v[92:95], v[138:141], v[200:203], v[92:95]
	v_mfma_f32_16x16x32_bf16 v[88:91], v[150:153], v[200:203], v[88:91]
	v_mfma_f32_16x16x32_bf16 v[76:79], v[138:141], v[208:211], v[76:79]
	v_mfma_f32_16x16x32_bf16 v[72:75], v[150:153], v[208:211], v[72:75]
	v_mfma_f32_16x16x32_bf16 v[124:127], v[142:145], v[178:181], v[124:127]
	v_mfma_f32_16x16x32_bf16 v[120:123], v[154:157], v[178:181], v[120:123]
	v_mfma_f32_16x16x32_bf16 v[108:111], v[142:145], v[186:189], v[108:111]
	v_mfma_f32_16x16x32_bf16 v[104:107], v[154:157], v[186:189], v[104:107]
	v_mfma_f32_16x16x32_bf16 v[92:95], v[142:145], v[204:207], v[92:95]
	v_mfma_f32_16x16x32_bf16 v[88:91], v[154:157], v[204:207], v[88:91]
	v_mfma_f32_16x16x32_bf16 v[76:79], v[142:145], v[212:215], v[76:79]
	v_mfma_f32_16x16x32_bf16 v[72:75], v[154:157], v[212:215], v[72:75]
	s_setprio 0
	s_setprio 1
	v_mfma_f32_16x16x32_bf16 v[116:119], v[158:161], v[174:177], v[116:119]
	v_mfma_f32_16x16x32_bf16 v[112:115], v[166:169], v[174:177], v[112:115]
	v_mfma_f32_16x16x32_bf16 v[100:103], v[158:161], v[182:185], v[100:103]
	v_mfma_f32_16x16x32_bf16 v[96:99], v[166:169], v[182:185], v[96:99]
	v_mfma_f32_16x16x32_bf16 v[84:87], v[158:161], v[200:203], v[84:87]
	v_mfma_f32_16x16x32_bf16 v[80:83], v[166:169], v[200:203], v[80:83]
	v_mfma_f32_16x16x32_bf16 v[68:71], v[158:161], v[208:211], v[68:71]
	v_mfma_f32_16x16x32_bf16 v[64:67], v[166:169], v[208:211], v[64:67]
	v_mfma_f32_16x16x32_bf16 v[116:119], v[162:165], v[178:181], v[116:119]
	v_mfma_f32_16x16x32_bf16 v[112:115], v[170:173], v[178:181], v[112:115]
	v_mfma_f32_16x16x32_bf16 v[100:103], v[162:165], v[186:189], v[100:103]
	v_mfma_f32_16x16x32_bf16 v[96:99], v[170:173], v[186:189], v[96:99]
	v_mfma_f32_16x16x32_bf16 v[84:87], v[162:165], v[204:207], v[84:87]
	v_mfma_f32_16x16x32_bf16 v[80:83], v[170:173], v[204:207], v[80:83]
	v_mfma_f32_16x16x32_bf16 v[68:71], v[162:165], v[212:215], v[68:71]
	v_mfma_f32_16x16x32_bf16 v[64:67], v[170:173], v[212:215], v[64:67]
	s_setprio 0
	s_barrier
	s_add_i32 s55, s55, s41
	s_mov_b32 m0, s55
	s_nop 0
	global_load_lds_dwordx4 v192, s[30:31]
	s_add_i32 m0, s55, 0x2000
	ds_read_b128 v[174:177], v149 offset:16384
	ds_read_b128 v[178:181], v149 offset:17408
	s_add_u32 s56, s30, 0x80000
	s_addc_u32 s57, s31, 0
	s_add_i32 s55, s58, s41
	global_load_lds_dwordx4 v128, s[30:31]
	s_mov_b32 m0, s55
	ds_read_b128 v[182:185], v149 offset:18432
	ds_read_b128 v[186:189], v149 offset:19456
	global_load_lds_dwordx4 v192, s[56:57]
	s_add_i32 m0, s55, 0x2000
	ds_read_b128 v[200:203], v149 offset:20480
	ds_read_b128 v[204:207], v149 offset:21504
	global_load_lds_dwordx4 v128, s[56:57]
	ds_read_b128 v[208:211], v149 offset:22528
	ds_read_b128 v[212:215], v149 offset:23552
	s_waitcnt vmcnt(6)
	s_waitcnt lgkmcnt(0)
	s_barrier
	s_setprio 1
	s_waitcnt lgkmcnt(0)
	v_mfma_f32_16x16x32_bf16 v[60:63], v[138:141], v[174:177], v[60:63]
	v_mfma_f32_16x16x32_bf16 v[56:59], v[150:153], v[174:177], v[56:59]
	v_mfma_f32_16x16x32_bf16 v[44:47], v[138:141], v[182:185], v[44:47]
	v_mfma_f32_16x16x32_bf16 v[40:43], v[150:153], v[182:185], v[40:43]
	v_mfma_f32_16x16x32_bf16 v[28:31], v[138:141], v[200:203], v[28:31]
	v_mfma_f32_16x16x32_bf16 v[24:27], v[150:153], v[200:203], v[24:27]
	v_mfma_f32_16x16x32_bf16 v[12:15], v[138:141], v[208:211], v[12:15]
	v_mfma_f32_16x16x32_bf16 v[8:11], v[150:153], v[208:211], v[8:11]
	v_mfma_f32_16x16x32_bf16 v[60:63], v[142:145], v[178:181], v[60:63]
	v_mfma_f32_16x16x32_bf16 v[56:59], v[154:157], v[178:181], v[56:59]
	v_mfma_f32_16x16x32_bf16 v[44:47], v[142:145], v[186:189], v[44:47]
	v_mfma_f32_16x16x32_bf16 v[40:43], v[154:157], v[186:189], v[40:43]
	v_mfma_f32_16x16x32_bf16 v[28:31], v[142:145], v[204:207], v[28:31]
	v_mfma_f32_16x16x32_bf16 v[24:27], v[154:157], v[204:207], v[24:27]
	v_mfma_f32_16x16x32_bf16 v[12:15], v[142:145], v[212:215], v[12:15]
	v_mfma_f32_16x16x32_bf16 v[8:11], v[154:157], v[212:215], v[8:11]
	s_setprio 0
	s_setprio 1
	v_mfma_f32_16x16x32_bf16 v[52:55], v[158:161], v[174:177], v[52:55]
	v_mfma_f32_16x16x32_bf16 v[48:51], v[166:169], v[174:177], v[48:51]
	v_mfma_f32_16x16x32_bf16 v[36:39], v[158:161], v[182:185], v[36:39]
	v_mfma_f32_16x16x32_bf16 v[32:35], v[166:169], v[182:185], v[32:35]
	v_mfma_f32_16x16x32_bf16 v[20:23], v[158:161], v[200:203], v[20:23]
	v_mfma_f32_16x16x32_bf16 v[16:19], v[166:169], v[200:203], v[16:19]
	v_mfma_f32_16x16x32_bf16 v[4:7], v[158:161], v[208:211], v[4:7]
	v_mfma_f32_16x16x32_bf16 v[0:3], v[166:169], v[208:211], v[0:3]
	v_mfma_f32_16x16x32_bf16 v[52:55], v[162:165], v[178:181], v[52:55]
	v_mfma_f32_16x16x32_bf16 v[48:51], v[170:173], v[178:181], v[48:51]
	v_mfma_f32_16x16x32_bf16 v[36:39], v[162:165], v[186:189], v[36:39]
	v_mfma_f32_16x16x32_bf16 v[32:35], v[170:173], v[186:189], v[32:35]
	v_mfma_f32_16x16x32_bf16 v[20:23], v[162:165], v[204:207], v[20:23]
	v_mfma_f32_16x16x32_bf16 v[16:19], v[170:173], v[204:207], v[16:19]
	v_mfma_f32_16x16x32_bf16 v[4:7], v[162:165], v[212:215], v[4:7]
	v_mfma_f32_16x16x32_bf16 v[0:3], v[170:173], v[212:215], v[0:3]
	s_setprio 0
	s_barrier
; #define PG8_STAGE(bufoff, gbase, voff) do { _Pragma("unroll") for (int _i = 0; _i < 2; ++_i) \
;         __builtin_amdgcn_global_load_lds((const unsigned*)((const char*)(gbase) + (voff)[_i]), (LAS unsigned*)(lds + (bufoff) + ldsw + _i * 8192), 16, 0, 0); } while (0)
; #define PG8_LDA(dst, b, h) do { _Pragma("unroll") for (int m = 0; m < 4; ++m) _Pragma("unroll") for (int k = 0; k < 2; ++k) dst[m][k] = *(const LAS bf16x8*)(lds + PG8_SA(b, h) + aoff + m * 2048 + k * 1024); } while (0)
; #define PG8_LDB(dst, b, h) do { _Pragma("unroll") for (int n = 0; n < 2; ++n) _Pragma("unroll") for (int k = 0; k < 2; ++k) dst[n][k] = *(const LAS bf16x8*)(lds + PG8_SB(b, h) + boff + n * 2048 + k * 1024); } while (0)
; #define PG8_MMA(ai, bj, At, Bt) do { __builtin_amdgcn_s_setprio(1); _Pragma("unroll") for (int m = 0; m < 4; ++m) _Pragma("unroll") for (int n = 0; n < 2; ++n) _Pragma("unroll") for (int k = 0; k < 2; ++k) \
;         acc[ai][bj][m][n] = __builtin_amdgcn_mfma_f32_16x16x32_bf16(Bt[n][k], At[m][k], acc[ai][bj][m][n], 0, 0, 0); __builtin_amdgcn_s_setprio(0); } while (0)
; #define PG8_WAIT_V(n) asm volatile("s_waitcnt vmcnt(" #n ")" ::: "memory")
; #define PG8_WAIT_L(n) asm volatile("s_waitcnt lgkmcnt(" #n ")" ::: "memory")
; #define PG8_BAR __builtin_amdgcn_s_barrier()
; #define PG8_SCHED __builtin_amdgcn_sched_barrier(0)
; template <class Epi, class Sched, bool ALIGN_EPI = false, bool SP2 = false>
; __device__ __forceinline__ void gemm_phase(LAS unsigned char* lds, const Gemm g, const Sched& S, const Epi& E, int wid) {
;     ...
;         for (int t = 0; t < nt; t += 2) {
;             const bool last = (t == nt - 2);
;             const char* a1 = cA + (size_t)(t + 1) * kstep;
;             const char* a2 = last ? nA : cA + (size_t)(t + 2) * kstep; const char* b2 = last ? nB : cB + (size_t)(t + 2) * kstep;
;     ...
;             PG8_LDB(B0, 1, 0); PG8_LDB(B1, 1, 1); PG8_SCHED; PG8_LDA(At, 1, 0); PG8_STAGE(PG8_SA(0, 1), a2 + hstepA, voffA);
;             PG8_WAIT_V(8); PG8_WAIT_L(0); PG8_BAR; PG8_MMA(0, 0, At, B0); PG8_MMA(0, 1, At, B1); PG8_BAR; PG8_SCHED;
;             PG8_LDA(At, 1, 1); PG8_STAGE(PG8_SB(1, 0), b3, voffB); PG8_STAGE(PG8_SB(1, 1), b3 + hstepB, voffB); PG8_STAGE(PG8_SA(1, 0), a3, voffA);
;             PG8_WAIT_V(8); PG8_WAIT_L(0); PG8_BAR; PG8_MMA(1, 0, At, B0); PG8_MMA(1, 1, At, B1); PG8_BAR; PG8_SCHED;
	s_add_i32 s55, 0, 0x18000
	s_add_i32 s56, 0, 0x1c000
	v_add_u32_e32 v154, s55, v147
	v_add_u32_e32 v170, s56, v147
	s_add_u32 s34, s34, 0x80000
	s_addc_u32 s35, s35, 0
	s_mov_b32 m0, s48
	s_add_u32 s100, s34, 0xfff80000
	s_addc_u32 s101, s35, -1
	s_mov_b32 m0, s42
	s_nop 0
	global_load_lds_dwordx4 v132, s[100:101]
	s_mov_b32 m0, s43
	ds_read_b128 v[138:141], v154
	ds_read_b128 v[142:145], v154 offset:1024
	ds_read_b128 v[150:153], v154 offset:2048
	ds_read_b128 v[154:157], v154 offset:3072
	global_load_lds_dwordx4 v130, s[100:101]
	s_mov_b32 m0, s48
	ds_read_b128 v[158:161], v170
	ds_read_b128 v[162:165], v170 offset:1024
	ds_read_b128 v[166:169], v170 offset:2048
	ds_read_b128 v[170:173], v170 offset:3072
	global_load_lds_dwordx4 v132, s[34:35]
	s_mov_b32 m0, s49
	ds_read_b128 v[174:177], v149 offset:32768
	ds_read_b128 v[178:181], v149 offset:33792
	ds_read_b128 v[182:185], v149 offset:34816
	ds_read_b128 v[186:189], v149 offset:35840
	global_load_lds_dwordx4 v130, s[34:35]
	ds_read_b128 v[200:203], v149 offset:36864
	ds_read_b128 v[204:207], v149 offset:37888
	ds_read_b128 v[208:211], v149 offset:38912
	ds_read_b128 v[212:215], v149 offset:39936
	s_waitcnt vmcnt(8)
	s_waitcnt lgkmcnt(0)
	s_barrier
	s_setprio 1
	s_waitcnt lgkmcnt(0)
	v_mfma_f32_16x16x32_bf16 v[124:127], v[138:141], v[174:177], v[124:127]
	v_mfma_f32_16x16x32_bf16 v[120:123], v[150:153], v[174:177], v[120:123]
	v_mfma_f32_16x16x32_bf16 v[108:111], v[138:141], v[182:185], v[108:111]
	v_mfma_f32_16x16x32_bf16 v[104:107], v[150:153], v[182:185], v[104:107]
	v_mfma_f32_16x16x32_bf16 v[92:95], v[138:141], v[200:203], v[92:95]
	v_mfma_f32_16x16x32_bf16 v[88:91], v[150:153], v[200:203], v[88:91]
	v_mfma_f32_16x16x32_bf16 v[76:79], v[138:141], v[208:211], v[76:79]
	v_mfma_f32_16x16x32_bf16 v[72:75], v[150:153], v[208:211], v[72:75]
	v_mfma_f32_16x16x32_bf16 v[124:127], v[142:145], v[178:181], v[124:127]
	v_mfma_f32_16x16x32_bf16 v[120:123], v[154:157], v[178:181], v[120:123]
	v_mfma_f32_16x16x32_bf16 v[108:111], v[142:145], v[186:189], v[108:111]
	v_mfma_f32_16x16x32_bf16 v[104:107], v[154:157], v[186:189], v[104:107]
	v_mfma_f32_16x16x32_bf16 v[92:95], v[142:145], v[204:207], v[92:95]
	v_mfma_f32_16x16x32_bf16 v[88:91], v[154:157], v[204:207], v[88:91]
	v_mfma_f32_16x16x32_bf16 v[76:79], v[142:145], v[212:215], v[76:79]
	v_mfma_f32_16x16x32_bf16 v[72:75], v[154:157], v[212:215], v[72:75]
	s_setprio 0
	s_setprio 1
	v_mfma_f32_16x16x32_bf16 v[116:119], v[158:161], v[174:177], v[116:119]
	v_mfma_f32_16x16x32_bf16 v[112:115], v[166:169], v[174:177], v[112:115]
	v_mfma_f32_16x16x32_bf16 v[100:103], v[158:161], v[182:185], v[100:103]
	v_mfma_f32_16x16x32_bf16 v[96:99], v[166:169], v[182:185], v[96:99]
	v_mfma_f32_16x16x32_bf16 v[84:87], v[158:161], v[200:203], v[84:87]
	v_mfma_f32_16x16x32_bf16 v[80:83], v[166:169], v[200:203], v[80:83]
	v_mfma_f32_16x16x32_bf16 v[68:71], v[158:161], v[208:211], v[68:71]
	v_mfma_f32_16x16x32_bf16 v[64:67], v[166:169], v[208:211], v[64:67]
	v_mfma_f32_16x16x32_bf16 v[116:119], v[162:165], v[178:181], v[116:119]
	v_mfma_f32_16x16x32_bf16 v[112:115], v[170:173], v[178:181], v[112:115]
	v_mfma_f32_16x16x32_bf16 v[100:103], v[162:165], v[186:189], v[100:103]
	v_mfma_f32_16x16x32_bf16 v[96:99], v[170:173], v[186:189], v[96:99]
	v_mfma_f32_16x16x32_bf16 v[84:87], v[162:165], v[204:207], v[84:87]
	v_mfma_f32_16x16x32_bf16 v[80:83], v[170:173], v[204:207], v[80:83]
	v_mfma_f32_16x16x32_bf16 v[68:71], v[162:165], v[212:215], v[68:71]
	v_mfma_f32_16x16x32_bf16 v[64:67], v[170:173], v[212:215], v[64:67]
	s_setprio 0
	s_barrier
	s_add_u32 s100, s30, 0x80
	s_addc_u32 s101, s31, 0
	s_add_i32 s34, s55, s41
	s_mov_b32 m0, s34
	s_nop 0
	global_load_lds_dwordx4 v192, s[100:101]
	s_add_i32 m0, s34, 0x2000
	ds_read_b128 v[174:177], v149 offset:49152
	ds_read_b128 v[178:181], v149 offset:50176
	s_add_u32 s30, s30, 0x80080
	s_addc_u32 s31, s31, 0
	s_add_i32 s34, s56, s41
	global_load_lds_dwordx4 v128, s[100:101]
	s_mov_b32 m0, s34
	ds_read_b128 v[182:185], v149 offset:51200
	ds_read_b128 v[186:189], v149 offset:52224
	global_load_lds_dwordx4 v192, s[30:31]
	s_add_i32 m0, s34, 0x2000
	ds_read_b128 v[200:203], v149 offset:53248
	ds_read_b128 v[204:207], v149 offset:54272
	global_load_lds_dwordx4 v128, s[30:31]
	ds_read_b128 v[208:211], v149 offset:55296
	ds_read_b128 v[212:215], v149 offset:56320
	s_waitcnt vmcnt(6)
	s_waitcnt lgkmcnt(0)
	s_barrier
	s_setprio 1
	s_waitcnt lgkmcnt(0)
	v_mfma_f32_16x16x32_bf16 v[60:63], v[138:141], v[174:177], v[60:63]
	v_mfma_f32_16x16x32_bf16 v[56:59], v[150:153], v[174:177], v[56:59]
	v_mfma_f32_16x16x32_bf16 v[44:47], v[138:141], v[182:185], v[44:47]
	v_mfma_f32_16x16x32_bf16 v[40:43], v[150:153], v[182:185], v[40:43]
	v_mfma_f32_16x16x32_bf16 v[28:31], v[138:141], v[200:203], v[28:31]
	v_mfma_f32_16x16x32_bf16 v[24:27], v[150:153], v[200:203], v[24:27]
	v_mfma_f32_16x16x32_bf16 v[12:15], v[138:141], v[208:211], v[12:15]
	v_mfma_f32_16x16x32_bf16 v[8:11], v[150:153], v[208:211], v[8:11]
	v_mfma_f32_16x16x32_bf16 v[60:63], v[142:145], v[178:181], v[60:63]
	v_mfma_f32_16x16x32_bf16 v[56:59], v[154:157], v[178:181], v[56:59]
	v_mfma_f32_16x16x32_bf16 v[44:47], v[142:145], v[186:189], v[44:47]
	v_mfma_f32_16x16x32_bf16 v[40:43], v[154:157], v[186:189], v[40:43]
	v_mfma_f32_16x16x32_bf16 v[28:31], v[142:145], v[204:207], v[28:31]
	v_mfma_f32_16x16x32_bf16 v[24:27], v[154:157], v[204:207], v[24:27]
	v_mfma_f32_16x16x32_bf16 v[12:15], v[142:145], v[212:215], v[12:15]
	v_mfma_f32_16x16x32_bf16 v[8:11], v[154:157], v[212:215], v[8:11]
	s_setprio 0
	s_setprio 1
	v_mfma_f32_16x16x32_bf16 v[52:55], v[158:161], v[174:177], v[52:55]
	v_mfma_f32_16x16x32_bf16 v[48:51], v[166:169], v[174:177], v[48:51]
	v_mfma_f32_16x16x32_bf16 v[36:39], v[158:161], v[182:185], v[36:39]
	v_mfma_f32_16x16x32_bf16 v[32:35], v[166:169], v[182:185], v[32:35]
	v_mfma_f32_16x16x32_bf16 v[20:23], v[158:161], v[200:203], v[20:23]
	v_mfma_f32_16x16x32_bf16 v[16:19], v[166:169], v[200:203], v[16:19]
	v_mfma_f32_16x16x32_bf16 v[4:7], v[158:161], v[208:211], v[4:7]
	v_mfma_f32_16x16x32_bf16 v[0:3], v[166:169], v[208:211], v[0:3]
	v_mfma_f32_16x16x32_bf16 v[52:55], v[162:165], v[178:181], v[52:55]
	v_mfma_f32_16x16x32_bf16 v[48:51], v[170:173], v[178:181], v[48:51]
	v_mfma_f32_16x16x32_bf16 v[36:39], v[162:165], v[186:189], v[36:39]
	v_mfma_f32_16x16x32_bf16 v[32:35], v[170:173], v[186:189], v[32:35]
	v_mfma_f32_16x16x32_bf16 v[20:23], v[162:165], v[204:207], v[20:23]
	v_mfma_f32_16x16x32_bf16 v[16:19], v[170:173], v[204:207], v[16:19]
	v_mfma_f32_16x16x32_bf16 v[4:7], v[162:165], v[212:215], v[4:7]
	v_mfma_f32_16x16x32_bf16 v[0:3], v[170:173], v[212:215], v[0:3]
	s_setprio 0
	s_barrier
	s_add_i32 s54, s54, 2
	s_add_u32 s10, s10, 0x100
	s_addc_u32 s11, s11, 0
	s_add_u32 s47, s47, 0x100
	s_addc_u32 s53, s53, 0
	s_cmp_gt_u32 s54, 29
	s_cbranch_scc0 .LBB0_488
	s_and_b64 vcc, exec, s[82:83]
	s_cbranch_vccz .LBB0_491
	s_barrier
